# stack2 + phase-7 weight-conversion items dealt starting at workgroup 88 so the halo workgroups (critical path) get one item each
# speedup vs baseline: 1.0082x; 1.0060x over previous
; #define LAS __attribute__((address_space(3)))
;     ...
;     int it0 = gw - (tr_base % NGW); if (it0 < 0) it0 += NGW; tr_base += nit;
; __global__ void __launch_bounds__(NWAVES * 64, 2) fwd_mega(Args args) {
;     ...
;             const int gwu = gw, NGWU = NGW; LAS float* scr = (LAS float*)(lds3 + wave * 16384); int trb = 0;
;             transpose_matrix(IN(29), 1024, 1952, W1in, L1P, 1024, scr, gwu, NGWU, lane, nullptr, trb);
;             transpose_matrix(IN(31), 256, 768, Wuq, 768, 256, scr, gwu, NGWU, lane, IN(30), trb);
;             transpose_matrix(IN(33), 128, 1024, Wukv, 1024, 256, scr, gwu, NGWU, lane, IN(32), trb, 2);
;             transpose_matrix(IN(34), 1024, 1024, W1out, 1024, 1024, scr, gwu, NGWU, lane, nullptr, trb);
;             transpose_matrix(IN(37), 1024, 5632, Wup1, 5632, 1024, scr, gwu, NGWU, lane, nullptr, trb, true);
;             transpose_matrix(IN(40), 2816, 1024, Wdn1, 1024, 2816, scr, gwu, NGWU, lane, nullptr, trb);
.LBB0_707:
	s_mov_b32 s98, s3
	v_readlane_b32 s99, v253, 0
	s_add_i32 s0, s99, 0xffffffa8
	s_add_i32 s1, s0, 0x100
	s_cmp_lt_i32 s0, 0
	s_cselect_b32 s0, s1, s0
	v_writelane_b32 v253, s0, 0
	s_lshl_b32 s0, s0, 3
	s_add_i32 s3, s0, s38
	v_readlane_b32 s0, v253, 2
	v_readlane_b32 s1, v253, 3
	s_add_u32 s34, s0, 0x1c00000
	s_addc_u32 s35, s1, 0
	s_lshl_b32 s0, s38, 14
	s_add_i32 s39, s0, 0
	s_ashr_i32 s0, s3, 31
	v_readlane_b32 s1, v253, 27
	s_and_b32 s0, s0, s1
	s_add_i32 s4, s0, s3
	s_cmpk_gt_i32 s4, 0x1ff
	v_lshrrev_b32_e32 v14, 3, v145
	v_lshlrev_b32_e32 v15, 4, v1
	s_cbranch_scc1 .LBB0_714
	v_readlane_b32 s0, v253, 4
	v_readlane_b32 s1, v253, 5
	s_load_dwordx2 s[8:9], s[0:1], 0xe8
	v_lshrrev_b32_e32 v1, 3, v145
	v_and_b32_e32 v2, 0x70, v15
	v_mul_u32_u24_e32 v4, 0x90, v145
	v_add_u32_e32 v5, s39, v2
	v_mov_b32_e32 v3, 0
	v_mul_u32_u24_e32 v6, 0x90, v1
	v_lshl_add_u64 v[2:3], s[34:35], 0, v[2:3]
	s_lshl_b32 s5, s4, 6
	s_movk_i32 s14, 0x7a0
	v_add_u32_e32 v6, v5, v6
	v_add_u32_e32 v7, s39, v4
	v_mov_b32_e32 v8, v145
	s_branch .LBB0_710

; __global__ void __launch_bounds__(NWAVES * 64, 2) fwd_mega(Args args) {
;     ...
;             for (int i = gwu * 64 + lane; i < 1024 * 16; i += NGWU * 64) { const int n = i >> 4, c = i & 15; *(v4u*)(Wukv + (size_t)n * 256 + 128 + c * 8) = (v4u){0u, 0u, 0u, 0u}; }
.LBB0_1037:
	s_mov_b32 s3, s98
	v_writelane_b32 v253, s99, 0
	v_lshl_or_b32 v1, s3, 6, v145
	s_movk_i32 s0, 0x4000
	v_cmp_gt_i32_e32 vcc, s0, v1
	s_and_saveexec_b64 s[6:7], vcc
	v_readlane_b32 s2, v253, 14
	v_readlane_b32 s3, v253, 15
	s_cbranch_execz .LBB0_1040
	v_readlane_b32 s0, v253, 4
	v_readlane_b32 s1, v253, 5
	s_load_dword s0, s[0:1], 0x168
	v_mov_b32_e32 v3, 0
	v_lshlrev_b32_e32 v4, 3, v1
	s_mov_b64 s[8:9], 0
	v_mov_b32_e32 v6, v3
	s_waitcnt lgkmcnt(0)
	s_lshl_b32 s0, s0, 12
	v_mov_b32_e32 v7, v3
	v_mov_b32_e32 v8, v3
	v_mov_b32_e32 v9, v3
	s_movk_i32 s1, 0x3fff
